# phase_stat: 2 rows of loads in flight (loop unrolled by 2, vmcnt(4))
# baseline (speedup 1.0000x reference)
; __device__ void phase_stat(const KP& p) {
;   int tid_ = threadIdx.x; asm volatile("" : "+v"(tid_));
;   const int lane = tid_ & 63, w = tid_ >> 6;
;   const bfr* hb = (const bfr*)(p.ws + OFF_HB);
;   float* rs = (float*)(p.ws + OFF_RS);
;   for (int row = p.bid * 8 + w; row < T_ROWS; row += p.nblk * 8) {
;     float ss = 0.f;
; #pragma unroll
;     for (int i = 0; i < 2; ++i) {
;       u32x4 v = *(const u32x4*)(hb + (size_t)row * DM + lane * 8 + 512 * i);
.LBB0_27:
	v_readlane_b32 s0, v255, 51
	v_readlane_b32 s1, v255, 52
	s_and_b64 vcc, exec, s[0:1]
	s_cbranch_vccz .LBB0_34
	s_waitcnt vmcnt(0)
	v_mov_b32_e32 v3, v156
	v_readlane_b32 s0, v255, 42
	s_lshl_b32 s0, s0, 3
	v_ashrrev_i32_e32 v2, 6, v3
	v_add_u32_e32 v0, s0, v2
	s_mov_b32 s1, 0x8400
	v_cmp_gt_i32_e32 vcc, s1, v0
	s_and_saveexec_b64 s[36:37], vcc
	s_cbranch_execz .LBB0_33
	v_and_b32_e32 v12, 63, v3
	v_and_b32_e32 v3, 64, v164
	v_add_u32_e32 v3, 64, v3
	v_xor_b32_e32 v4, 32, v164
	v_cmp_lt_i32_e32 vcc, v4, v3
	v_readlane_b32 s2, v255, 43
	v_readlane_b32 s3, v255, 44
	v_cndmask_b32_e32 v4, v164, v4, vcc
	v_lshlrev_b32_e32 v6, 2, v4
	v_xor_b32_e32 v4, 16, v164
	v_cmp_lt_i32_e32 vcc, v4, v3
	s_lshl_b32 s38, s2, 3
	s_ashr_i32 s1, s0, 31
	v_cndmask_b32_e32 v4, v164, v4, vcc
	v_lshlrev_b32_e32 v7, 2, v4
	v_xor_b32_e32 v4, 8, v164
	v_cmp_lt_i32_e32 vcc, v4, v3
	v_readlane_b32 s2, v255, 45
	v_readlane_b32 s3, v255, 46
	v_cndmask_b32_e32 v4, v164, v4, vcc
	s_waitcnt lgkmcnt(0)
	v_lshlrev_b32_e32 v8, 2, v4
	v_xor_b32_e32 v4, 4, v164
	v_cmp_lt_i32_e32 vcc, v4, v3
	s_ashr_i32 s39, s38, 31
	s_lshl_b64 s[40:41], s[38:39], 2
	v_cndmask_b32_e32 v4, v164, v4, vcc
	v_lshlrev_b32_e32 v9, 2, v4
	v_xor_b32_e32 v4, 2, v164
	v_cmp_lt_i32_e32 vcc, v4, v3
	s_lshl_b64 s[42:43], s[38:39], 11
	s_mov_b64 s[44:45], 0
	v_cndmask_b32_e32 v4, v164, v4, vcc
	v_lshlrev_b32_e32 v10, 2, v4
	v_xor_b32_e32 v4, 1, v164
	v_cmp_lt_i32_e32 vcc, v4, v3
	s_nop 1
	v_cndmask_b32_e32 v3, v164, v4, vcc
	v_lshlrev_b32_e32 v11, 2, v3
	v_ashrrev_i32_e32 v3, 31, v2
	v_lshl_add_u64 v[4:5], v[2:3], 0, s[0:1]
	v_lshl_add_u64 v[2:3], v[4:5], 2, s[2:3]
	v_lshlrev_b64 v[4:5], 11, v[4:5]
	s_mov_b64 s[0:1], 0x4200000
	v_lshl_or_b32 v4, v12, 4, v4
	v_lshl_add_u64 v[2:3], v[2:3], 0, s[0:1]
	v_lshl_add_u64 v[4:5], s[2:3], 0, v[4:5]
	s_mov_b64 s[0:1], 0x400
	v_cmp_eq_u32_e32 vcc, 0, v12
	v_lshl_add_u64 v[4:5], v[4:5], 0, s[0:1]
	global_load_dwordx4 v[12:15], v[4:5], off offset:-1024
	global_load_dwordx4 v[16:19], v[4:5], off
	global_load_dword v46, v[4:5], off
	v_lshl_add_u64 v[44:45], v[4:5], 0, s[42:43]
	global_load_dwordx4 v[48:51], v[44:45], off offset:-1024
	global_load_dwordx4 v[52:55], v[44:45], off
	global_load_dword v46, v[4:5], off
	s_branch .LBB0_31

; __device__ void phase_stat(const KP& p) {
;     ...
;   for (int row = p.bid * 8 + w; row < T_ROWS; row += p.nblk * 8) {
;     float ss = 0.f;
; #pragma unroll
;     for (int i = 0; i < 2; ++i) {
;       u32x4 v = *(const u32x4*)(hb + (size_t)row * DM + lane * 8 + 512 * i);
; #pragma unroll
;       for (int e = 0; e < 4; ++e) {
;         float a = __uint_as_float(v[e] << 16), b = __uint_as_float(v[e] & 0xffff0000u);
;         ss += a * a + b * b;
;       }
;     }
;     ss = wave_sum(ss);
;     if (lane == 0) rs[row] = rsqrtf(ss * (1.f / DM) + EPSF);
;   }
.LBB0_31:
	s_waitcnt lgkmcnt(0)
	s_waitcnt vmcnt(4)
	v_mov_b32_e32 v36, v12
	v_mov_b32_e32 v37, v13
	v_mov_b32_e32 v38, v14
	v_mov_b32_e32 v39, v15
	v_mov_b32_e32 v40, v16
	v_mov_b32_e32 v41, v17
	v_mov_b32_e32 v42, v18
	v_mov_b32_e32 v43, v19
	v_lshl_add_u64 v[44:45], v[4:5], 0, s[42:43]
	v_lshl_add_u64 v[44:45], v[44:45], 0, s[42:43]
	global_load_dwordx4 v[12:15], v[44:45], off offset:-1024
	global_load_dwordx4 v[16:19], v[44:45], off
	v_lshlrev_b32_e32 v20, 16, v36
	v_and_b32_e32 v36, 0xffff0000, v36
	v_lshlrev_b32_e32 v21, 16, v37
	v_and_b32_e32 v37, 0xffff0000, v37
	v_lshlrev_b32_e32 v22, 16, v38
	v_and_b32_e32 v38, 0xffff0000, v38
	v_mul_f32_e32 v36, v36, v36
	v_mul_f32_e32 v37, v37, v37
	v_lshlrev_b32_e32 v23, 16, v39
	v_and_b32_e32 v39, 0xffff0000, v39
	v_mul_f32_e32 v38, v38, v38
	v_fmac_f32_e32 v36, v20, v20
	v_fmac_f32_e32 v37, v21, v21
	v_lshlrev_b32_e32 v24, 16, v40
	v_and_b32_e32 v40, 0xffff0000, v40
	v_mul_f32_e32 v39, v39, v39
	v_fmac_f32_e32 v38, v22, v22
	v_add_f32_e32 v36, v36, v37
	v_lshlrev_b32_e32 v25, 16, v41
	v_and_b32_e32 v41, 0xffff0000, v41
	v_mul_f32_e32 v40, v40, v40
	v_fmac_f32_e32 v39, v23, v23
	v_add_f32_e32 v36, v38, v36
	v_lshlrev_b32_e32 v26, 16, v42
	v_and_b32_e32 v42, 0xffff0000, v42
	v_mul_f32_e32 v41, v41, v41
	v_fmac_f32_e32 v40, v24, v24
	v_add_f32_e32 v36, v39, v36
	v_lshlrev_b32_e32 v27, 16, v43
	v_and_b32_e32 v43, 0xffff0000, v43
	v_mul_f32_e32 v42, v42, v42
	v_fmac_f32_e32 v41, v25, v25
	v_add_f32_e32 v36, v40, v36
	v_mul_f32_e32 v43, v43, v43
	v_fmac_f32_e32 v42, v26, v26
	v_add_f32_e32 v36, v41, v36
	v_add_f32_e32 v36, v42, v36
	v_fmac_f32_e32 v43, v27, v27
	v_add_f32_e32 v36, v43, v36
	ds_bpermute_b32 v37, v6, v36
	s_waitcnt lgkmcnt(0)
	v_add_f32_e32 v36, v36, v37
	ds_bpermute_b32 v37, v7, v36
	s_waitcnt lgkmcnt(0)
	v_add_f32_e32 v36, v36, v37
	ds_bpermute_b32 v37, v8, v36
	s_waitcnt lgkmcnt(0)
	v_add_f32_e32 v36, v36, v37
	ds_bpermute_b32 v37, v9, v36
	s_waitcnt lgkmcnt(0)
	v_add_f32_e32 v36, v36, v37
	ds_bpermute_b32 v37, v10, v36
	s_waitcnt lgkmcnt(0)
	v_add_f32_e32 v36, v36, v37
	ds_bpermute_b32 v37, v11, v36
	s_and_saveexec_b64 s[46:47], vcc
	s_cbranch_execz .Lstat_a_adv
	s_waitcnt lgkmcnt(0)
	v_add_f32_e32 v36, v36, v37
	v_fmamk_f32 v36, v36, 0x3a800000, v162
	s_mov_b32 s0, 0x800000
	v_mul_f32_e32 v37, 0x4b800000, v36
	v_cmp_gt_f32_e64 s[0:1], s0, v36
	s_nop 1
	v_cndmask_b32_e64 v36, v36, v37, s[0:1]
	v_rsq_f32_e32 v36, v36
	s_nop 0
	v_mul_f32_e32 v37, 0x45800000, v36
	v_cndmask_b32_e64 v36, v36, v37, s[0:1]
	global_store_dword v[2:3], v36, off

; __device__ void phase_stat(const KP& p) {
;     ...
;   for (int row = p.bid * 8 + w; row < T_ROWS; row += p.nblk * 8) {
;     float ss = 0.f;
; #pragma unroll
;     for (int i = 0; i < 2; ++i) {
;       u32x4 v = *(const u32x4*)(hb + (size_t)row * DM + lane * 8 + 512 * i);
; #pragma unroll
;       for (int e = 0; e < 4; ++e) {
;         float a = __uint_as_float(v[e] << 16), b = __uint_as_float(v[e] & 0xffff0000u);
;         ss += a * a + b * b;
;       }
;     }
;     ss = wave_sum(ss);
;     if (lane == 0) rs[row] = rsqrtf(ss * (1.f / DM) + EPSF);
;   }
.Lstat_b:
	s_waitcnt lgkmcnt(0)
	s_waitcnt vmcnt(4)
	v_mov_b32_e32 v36, v48
	v_mov_b32_e32 v37, v49
	v_mov_b32_e32 v38, v50
	v_mov_b32_e32 v39, v51
	v_mov_b32_e32 v40, v52
	v_mov_b32_e32 v41, v53
	v_mov_b32_e32 v42, v54
	v_mov_b32_e32 v43, v55
	v_lshl_add_u64 v[44:45], v[4:5], 0, s[42:43]
	v_lshl_add_u64 v[44:45], v[44:45], 0, s[42:43]
	global_load_dwordx4 v[48:51], v[44:45], off offset:-1024
	global_load_dwordx4 v[52:55], v[44:45], off
	v_lshlrev_b32_e32 v20, 16, v36
	v_and_b32_e32 v36, 0xffff0000, v36
	v_lshlrev_b32_e32 v21, 16, v37
	v_and_b32_e32 v37, 0xffff0000, v37
	v_lshlrev_b32_e32 v22, 16, v38
	v_and_b32_e32 v38, 0xffff0000, v38
	v_mul_f32_e32 v36, v36, v36
	v_mul_f32_e32 v37, v37, v37
	v_lshlrev_b32_e32 v23, 16, v39
	v_and_b32_e32 v39, 0xffff0000, v39
	v_mul_f32_e32 v38, v38, v38
	v_fmac_f32_e32 v36, v20, v20
	v_fmac_f32_e32 v37, v21, v21
	v_lshlrev_b32_e32 v24, 16, v40
	v_and_b32_e32 v40, 0xffff0000, v40
	v_mul_f32_e32 v39, v39, v39
	v_fmac_f32_e32 v38, v22, v22
	v_add_f32_e32 v36, v36, v37
	v_lshlrev_b32_e32 v25, 16, v41
	v_and_b32_e32 v41, 0xffff0000, v41
	v_mul_f32_e32 v40, v40, v40
	v_fmac_f32_e32 v39, v23, v23
	v_add_f32_e32 v36, v38, v36
	v_lshlrev_b32_e32 v26, 16, v42
	v_and_b32_e32 v42, 0xffff0000, v42
	v_mul_f32_e32 v41, v41, v41
	v_fmac_f32_e32 v40, v24, v24
	v_add_f32_e32 v36, v39, v36
	v_lshlrev_b32_e32 v27, 16, v43
	v_and_b32_e32 v43, 0xffff0000, v43
	v_mul_f32_e32 v42, v42, v42
	v_fmac_f32_e32 v41, v25, v25
	v_add_f32_e32 v36, v40, v36
	v_mul_f32_e32 v43, v43, v43
	v_fmac_f32_e32 v42, v26, v26
	v_add_f32_e32 v36, v41, v36
	v_add_f32_e32 v36, v42, v36
	v_fmac_f32_e32 v43, v27, v27
	v_add_f32_e32 v36, v43, v36
	ds_bpermute_b32 v37, v6, v36
	s_waitcnt lgkmcnt(0)
	v_add_f32_e32 v36, v36, v37
	ds_bpermute_b32 v37, v7, v36
	s_waitcnt lgkmcnt(0)
	v_add_f32_e32 v36, v36, v37
	ds_bpermute_b32 v37, v8, v36
	s_waitcnt lgkmcnt(0)
	v_add_f32_e32 v36, v36, v37
	ds_bpermute_b32 v37, v9, v36
	s_waitcnt lgkmcnt(0)
	v_add_f32_e32 v36, v36, v37
	ds_bpermute_b32 v37, v10, v36
	s_waitcnt lgkmcnt(0)
	v_add_f32_e32 v36, v36, v37
	ds_bpermute_b32 v37, v11, v36
	s_and_saveexec_b64 s[46:47], vcc
	s_cbranch_execz .LBB0_30
	s_waitcnt lgkmcnt(0)
	v_add_f32_e32 v36, v36, v37
	v_fmamk_f32 v36, v36, 0x3a800000, v162
	s_mov_b32 s0, 0x800000
	v_mul_f32_e32 v37, 0x4b800000, v36
	v_cmp_gt_f32_e64 s[0:1], s0, v36
	s_nop 1
	v_cndmask_b32_e64 v36, v36, v37, s[0:1]
	v_rsq_f32_e32 v36, v36
	s_nop 0
	v_mul_f32_e32 v37, 0x45800000, v36
	v_cndmask_b32_e64 v36, v36, v37, s[0:1]
	global_store_dword v[2:3], v36, off
	s_branch .LBB0_30
